# attention partial-output stores non-temporal
# speedup vs baseline: 1.0061x; 1.0061x over previous
; #define LAS __attribute__((address_space(3)))
; __device__ __forceinline__ float bflo(unsigned u) { return __uint_as_float(u << 16); }
; __device__ __forceinline__ void attn_phase(LAS unsigned char* lds, const bf16* PROJ, const bf16* Ygate, bf16* OG0, bf16* OG1, bf16* OG2, float* LSE, const float* qnw, const float* knw, int bx, int G) {
;     ...
;         const float lse = mx + __logf(sum), inv = 1.f / sum;
;         f32x4 oacc[4];
; #pragma unroll
;         for (int dt = 0; dt < 4; ++dt) oacc[dt] = (f32x4){0.f, 0.f, 0.f, 0.f};
; #pragma unroll
;         for (int k2 = 0; k2 < 5; ++k2) {
;             const int T0 = w + 2 * k2;
;             if (T0 + 1 >= tlo) {
;                 v4u bpu; bpu.x = pk2(sc[2 * k2][0], sc[2 * k2][1]); bpu.y = pk2(sc[2 * k2][2], sc[2 * k2][3]);
;                 if (k2 < 4) { bpu.z = pk2(sc[(2 * k2 + 1) % 9][0], sc[(2 * k2 + 1) % 9][1]); bpu.w = pk2(sc[(2 * k2 + 1) % 9][2], sc[(2 * k2 + 1) % 9][3]); } else { bpu.z = 0u; bpu.w = 0u; }
;                 const bf16x8 bp = __builtin_bit_cast(bf16x8, bpu);
;                 const LAS bf16* vb = Vs + (16 * T0 + 4 * g4 + (l16 >> 2)) * 80 + 8 * (l16 & 3);
; #pragma unroll
;                 for (int dt = 0; dt < 4; ++dt) {
;                     const int co = 32 * (dt >> 1) + 4 * (dt & 1);
;                     const v4i16_t lo = __builtin_amdgcn_ds_read_tr16_b64_v4i16((LAS v4i16_t*)(vb + co));
;                     v4i16_t hi = (v4i16_t){0, 0, 0, 0};
;                     if (k2 < 4) hi = __builtin_amdgcn_ds_read_tr16_b64_v4i16((LAS v4i16_t*)(vb + 16 * 80 + co));
;                     oacc[dt] = mfma16((bf16x8){lo[0], lo[1], lo[2], lo[3], hi[0], hi[1], hi[2], hi[3]}, bp, oacc[dt]);
;                 }
;             }
;         }
; #pragma unroll
;         for (int j = 0; j < 2; ++j) {
;             const size_t off = qrow * 1024 + (size_t)h * 64 + 32 * j + 8 * g4; const v4u g = gg[j]; const f32x4 e = oacc[2 * j], o = oacc[2 * j + 1];
;             v4u y;
;             y.x = pk2(e[0] * inv * bflo(g.x), e[1] * inv * bfhi(g.x)); y.y = pk2(e[2] * inv * bflo(g.y), e[3] * inv * bfhi(g.y));
;             y.z = pk2(o[0] * inv * bflo(g.z), o[1] * inv * bfhi(g.z)); y.w = pk2(o[2] * inv * bflo(g.w), o[3] * inv * bfhi(g.w));
;             *(v4u*)(OG + off) = y;
;         }
;         if (g4 == 0) LSE[((size_t)gi * 8192 + qrow) * 16 + h] = lse;
.LBB0_306:
	v_readlane_b32 s0, v255, 26
	v_readlane_b32 s20, v252, 39
	s_waitcnt lgkmcnt(0)
	v_add_f32_e32 v1, v135, v165
	s_cmp_eq_u32 s2, 1
	v_readlane_b32 s1, v255, 27
	v_readlane_b32 s21, v252, 40
	s_cselect_b32 s20, s20, s0
	s_cselect_b32 s21, s21, s1
	v_div_scale_f32 v2, s[0:1], v1, v1, 1.0
	v_rcp_f32_e32 v3, v2
	s_waitcnt vmcnt(1)
	v_lshlrev_b32_e32 v152, 16, v88
	v_and_b32_e32 v153, 0xffff0000, v88
	s_mov_b64 s[82:83], s[62:63]
	v_fma_f32 v135, -v2, v3, 1.0
	v_fmac_f32_e32 v3, v135, v3
	v_div_scale_f32 v135, vcc, 1.0, v1, 1.0
	v_mul_f32_e32 v150, v135, v3
	v_fma_f32 v151, -v2, v150, v135
	v_fmac_f32_e32 v150, v151, v3
	v_fma_f32 v2, -v2, v150, v135
	v_div_fmas_f32 v2, v2, v3, v150
	v_div_fixup_f32 v2, v2, v1, 1.0
	v_pk_mul_f32 v[104:105], v[2:3], v[104:105] op_sel_hi:[0,1]
	v_pk_mul_f32 v[104:105], v[104:105], v[152:153]
	s_cmp_eq_u32 s2, 0
	v_cvt_pk_bf16_f32 v88, v104, v105
	v_pk_mul_f32 v[104:105], v[2:3], v[106:107] op_sel_hi:[0,1]
	v_lshlrev_b32_e32 v106, 16, v89
	v_and_b32_e32 v107, 0xffff0000, v89
	v_pk_mul_f32 v[104:105], v[104:105], v[106:107]
	s_mov_b64 s[80:81], s[60:61]
	v_cvt_pk_bf16_f32 v89, v104, v105
	v_pk_mul_f32 v[100:101], v[2:3], v[100:101] op_sel_hi:[0,1]
	v_lshlrev_b32_e32 v104, 16, v90
	v_and_b32_e32 v105, 0xffff0000, v90
	s_cselect_b32 s1, s81, s21
	s_cselect_b32 s0, s80, s20
	v_pk_mul_f32 v[100:101], v[100:101], v[104:105]
	v_lshl_add_u64 v[150:151], s[0:1], 0, v[162:163]
	s_lshl_b32 s26, s3, 1
	v_cvt_pk_bf16_f32 v90, v100, v101
	v_pk_mul_f32 v[100:101], v[2:3], v[102:103] op_sel_hi:[0,1]
	v_lshlrev_b32_e32 v102, 16, v91
	v_and_b32_e32 v103, 0xffff0000, v91
	v_lshl_add_u64 v[150:151], v[150:151], 0, s[26:27]
	v_mov_b32_e32 v135, v0
	v_pk_mul_f32 v[100:101], v[100:101], v[102:103]
	v_lshl_add_u64 v[150:151], v[150:151], 0, v[134:135]
	v_cvt_pk_bf16_f32 v91, v100, v101
	global_store_dwordx4 v[150:151], v[88:91], off nt
	s_nop 1
	v_pk_mul_f32 v[88:89], v[2:3], v[96:97] op_sel_hi:[0,1]
	s_waitcnt vmcnt(1)
	v_lshlrev_b32_e32 v90, 16, v84
	v_and_b32_e32 v91, 0xffff0000, v84
	v_pk_mul_f32 v[88:89], v[88:89], v[90:91]
	v_lshlrev_b32_e32 v90, 16, v85
	v_cvt_pk_bf16_f32 v84, v88, v89
	v_pk_mul_f32 v[88:89], v[2:3], v[98:99] op_sel_hi:[0,1]
	v_and_b32_e32 v91, 0xffff0000, v85
	v_pk_mul_f32 v[88:89], v[88:89], v[90:91]
	v_lshlrev_b32_e32 v90, 16, v86
	v_cvt_pk_bf16_f32 v85, v88, v89
	v_pk_mul_f32 v[88:89], v[2:3], v[92:93] op_sel_hi:[0,1]
	v_and_b32_e32 v91, 0xffff0000, v86
	v_pk_mul_f32 v[88:89], v[88:89], v[90:91]
	v_pk_mul_f32 v[2:3], v[2:3], v[94:95] op_sel_hi:[0,1]
	v_cvt_pk_bf16_f32 v86, v88, v89
	v_lshlrev_b32_e32 v88, 16, v87
	v_and_b32_e32 v89, 0xffff0000, v87
	v_pk_mul_f32 v[2:3], v[2:3], v[88:89]
	s_nop 0
	v_cvt_pk_bf16_f32 v87, v2, v3
	global_store_dwordx4 v[150:151], v[84:87], off offset:64 nt
	s_and_saveexec_b64 s[0:1], s[40:41]
	s_cbranch_execz .LBB0_308
	v_cmp_gt_f32_e32 vcc, s33, v1
	s_mov_b32 s3, 0x3f317217
	v_readlane_b32 s20, v251, 25
	v_cndmask_b32_e64 v2, 0, 32, vcc
	v_ldexp_f32 v1, v1, v2
	v_log_f32_e32 v1, v1
	v_cndmask_b32_e32 v2, 0, v194, vcc
	v_readlane_b32 s21, v251, 26
	v_mul_f32_e32 v3, 0x3f317217, v1
	v_fma_f32 v3, v1, s3, -v3
	s_mov_b32 s3, 0x7f800000
	v_fmac_f32_e32 v3, 0x3377d1cf, v1
	v_cmp_lt_f32_e64 vcc, |v1|, s3
	s_ashr_i32 s3, s2, 31
	v_fmac_f32_e32 v3, 0x3f317217, v1
	s_lshl_b64 s[2:3], s[2:3], 19
	v_cndmask_b32_e32 v1, v1, v3, vcc
	s_add_u32 s2, s20, s2
	v_sub_f32_e32 v1, v1, v2
	s_addc_u32 s3, s21, s3
	v_lshlrev_b64 v[2:3], 6, v[136:137]
	v_lshl_add_u64 v[2:3], s[2:3], 0, v[2:3]
	s_lshl_b32 s26, s53, 2
	v_add_f32_e32 v1, v164, v1
	v_lshl_add_u64 v[2:3], v[2:3], 0, s[26:27]
	global_store_dword v[2:3], v1, off

; #define LAS __attribute__((address_space(3)))
; __device__ __forceinline__ float bflo(unsigned u) { return __uint_as_float(u << 16); }
; __device__ __forceinline__ void attn_phase(LAS unsigned char* lds, const bf16* PROJ, const bf16* Ygate, bf16* OG0, bf16* OG1, bf16* OG2, float* LSE, const float* qnw, const float* knw, int bx, int G) {
;     ...
;         const float lse = mx + __logf(sum), inv = 1.f / sum;
;         f32x4 oacc[4];
; #pragma unroll
;         for (int dt = 0; dt < 4; ++dt) oacc[dt] = (f32x4){0.f, 0.f, 0.f, 0.f};
; #pragma unroll
;         for (int k2 = 0; k2 < 5; ++k2) {
;             const int T0 = w + 2 * k2;
;             if (T0 + 1 >= tlo) {
;                 v4u bpu; bpu.x = pk2(sc[2 * k2][0], sc[2 * k2][1]); bpu.y = pk2(sc[2 * k2][2], sc[2 * k2][3]);
;                 if (k2 < 4) { bpu.z = pk2(sc[(2 * k2 + 1) % 9][0], sc[(2 * k2 + 1) % 9][1]); bpu.w = pk2(sc[(2 * k2 + 1) % 9][2], sc[(2 * k2 + 1) % 9][3]); } else { bpu.z = 0u; bpu.w = 0u; }
;                 const bf16x8 bp = __builtin_bit_cast(bf16x8, bpu);
;                 const LAS bf16* vb = Vs + (16 * T0 + 4 * g4 + (l16 >> 2)) * 80 + 8 * (l16 & 3);
; #pragma unroll
;                 for (int dt = 0; dt < 4; ++dt) {
;                     const int co = 32 * (dt >> 1) + 4 * (dt & 1);
;                     const v4i16_t lo = __builtin_amdgcn_ds_read_tr16_b64_v4i16((LAS v4i16_t*)(vb + co));
;                     v4i16_t hi = (v4i16_t){0, 0, 0, 0};
;                     if (k2 < 4) hi = __builtin_amdgcn_ds_read_tr16_b64_v4i16((LAS v4i16_t*)(vb + 16 * 80 + co));
;                     oacc[dt] = mfma16((bf16x8){lo[0], lo[1], lo[2], lo[3], hi[0], hi[1], hi[2], hi[3]}, bp, oacc[dt]);
;                 }
;             }
;         }
; #pragma unroll
;         for (int j = 0; j < 2; ++j) {
;             const size_t off = qrow * 1024 + (size_t)h * 64 + 32 * j + 8 * g4; const v4u g = gg[j]; const f32x4 e = oacc[2 * j], o = oacc[2 * j + 1];
;             v4u y;
;             y.x = pk2(e[0] * inv * bflo(g.x), e[1] * inv * bfhi(g.x)); y.y = pk2(e[2] * inv * bflo(g.y), e[3] * inv * bfhi(g.y));
;             y.z = pk2(o[0] * inv * bflo(g.z), o[1] * inv * bfhi(g.z)); y.w = pk2(o[2] * inv * bflo(g.w), o[3] * inv * bfhi(g.w));
;             *(v4u*)(OG + off) = y;
;         }
;         if (g4 == 0) LSE[((size_t)gi * 8192 + qrow) * 16 + h] = lse;
.LBB0_348:
	v_readlane_b32 s0, v255, 26
	v_readlane_b32 s20, v252, 39
	s_waitcnt lgkmcnt(0)
	v_add_f32_e32 v1, v135, v165
	s_cmp_eq_u32 s2, 1
	v_readlane_b32 s1, v255, 27
	v_readlane_b32 s21, v252, 40
	s_cselect_b32 s20, s20, s0
	s_cselect_b32 s21, s21, s1
	v_div_scale_f32 v2, s[0:1], v1, v1, 1.0
	v_rcp_f32_e32 v3, v2
	s_mov_b64 s[82:83], s[62:63]
	s_cmp_eq_u32 s2, 0
	s_mov_b64 s[80:81], s[60:61]
	v_fma_f32 v135, -v2, v3, 1.0
	v_fmac_f32_e32 v3, v135, v3
	v_div_scale_f32 v135, vcc, 1.0, v1, 1.0
	v_mul_f32_e32 v150, v135, v3
	v_fma_f32 v151, -v2, v150, v135
	v_fmac_f32_e32 v150, v151, v3
	s_cselect_b32 s1, s81, s21
	s_cselect_b32 s0, s80, s20
	v_fma_f32 v2, -v2, v150, v135
	v_div_fmas_f32 v2, v2, v3, v150
	v_lshl_add_u64 v[150:151], s[0:1], 0, v[162:163]
	s_lshl_b32 s26, s3, 1
	v_div_fixup_f32 v2, v2, v1, 1.0
	v_lshl_add_u64 v[150:151], v[150:151], 0, s[26:27]
	v_mov_b32_e32 v135, v0
	v_lshl_add_u64 v[134:135], v[150:151], 0, v[134:135]
	v_pk_mul_f32 v[104:105], v[2:3], v[104:105] op_sel_hi:[0,1]
	s_waitcnt vmcnt(1)
	v_lshlrev_b32_e32 v150, 16, v88
	v_and_b32_e32 v151, 0xffff0000, v88
	v_pk_mul_f32 v[104:105], v[104:105], v[150:151]
	v_pk_mul_f32 v[100:101], v[2:3], v[100:101] op_sel_hi:[0,1]
	v_cvt_pk_bf16_f32 v88, v104, v105
	v_pk_mul_f32 v[104:105], v[2:3], v[106:107] op_sel_hi:[0,1]
	v_lshlrev_b32_e32 v106, 16, v89
	v_and_b32_e32 v107, 0xffff0000, v89
	v_pk_mul_f32 v[104:105], v[104:105], v[106:107]
	s_nop 0
	v_cvt_pk_bf16_f32 v89, v104, v105
	v_lshlrev_b32_e32 v104, 16, v90
	v_and_b32_e32 v105, 0xffff0000, v90
	v_pk_mul_f32 v[100:101], v[100:101], v[104:105]
	s_nop 0
	v_cvt_pk_bf16_f32 v90, v100, v101
	v_pk_mul_f32 v[100:101], v[2:3], v[102:103] op_sel_hi:[0,1]
	v_lshlrev_b32_e32 v102, 16, v91
	v_and_b32_e32 v103, 0xffff0000, v91
	v_pk_mul_f32 v[100:101], v[100:101], v[102:103]
	s_nop 0
	v_cvt_pk_bf16_f32 v91, v100, v101
	global_store_dwordx4 v[134:135], v[88:91], off nt
	s_nop 1
	v_pk_mul_f32 v[88:89], v[2:3], v[96:97] op_sel_hi:[0,1]
	s_waitcnt vmcnt(1)
	v_lshlrev_b32_e32 v90, 16, v84
	v_and_b32_e32 v91, 0xffff0000, v84
	v_pk_mul_f32 v[88:89], v[88:89], v[90:91]
	v_lshlrev_b32_e32 v90, 16, v85
	v_cvt_pk_bf16_f32 v84, v88, v89
	v_pk_mul_f32 v[88:89], v[2:3], v[98:99] op_sel_hi:[0,1]
	v_and_b32_e32 v91, 0xffff0000, v85
	v_pk_mul_f32 v[88:89], v[88:89], v[90:91]
	v_lshlrev_b32_e32 v90, 16, v86
	v_cvt_pk_bf16_f32 v85, v88, v89
	v_pk_mul_f32 v[88:89], v[2:3], v[92:93] op_sel_hi:[0,1]
	v_and_b32_e32 v91, 0xffff0000, v86
	v_pk_mul_f32 v[88:89], v[88:89], v[90:91]
	v_pk_mul_f32 v[2:3], v[2:3], v[94:95] op_sel_hi:[0,1]
	v_cvt_pk_bf16_f32 v86, v88, v89
	v_lshlrev_b32_e32 v88, 16, v87
	v_and_b32_e32 v89, 0xffff0000, v87
	v_pk_mul_f32 v[2:3], v[2:3], v[88:89]
	s_nop 0
	v_cvt_pk_bf16_f32 v87, v2, v3
	global_store_dwordx4 v[134:135], v[84:87], off offset:64 nt
	s_and_saveexec_b64 s[0:1], s[40:41]
	s_cbranch_execz .LBB0_267
	v_cmp_gt_f32_e32 vcc, s33, v1
	s_mov_b32 s3, 0x3f317217
	v_readlane_b32 s20, v251, 25
	v_cndmask_b32_e64 v2, 0, 32, vcc
	v_ldexp_f32 v1, v1, v2
	v_log_f32_e32 v1, v1
	v_cndmask_b32_e32 v2, 0, v194, vcc
	v_readlane_b32 s21, v251, 26
	v_mul_f32_e32 v3, 0x3f317217, v1
	v_fma_f32 v3, v1, s3, -v3
	s_mov_b32 s3, 0x7f800000
	v_fmac_f32_e32 v3, 0x3377d1cf, v1
	v_cmp_lt_f32_e64 vcc, |v1|, s3
	s_ashr_i32 s3, s2, 31
	v_fmac_f32_e32 v3, 0x3f317217, v1
	s_lshl_b64 s[2:3], s[2:3], 19
	v_cndmask_b32_e32 v1, v1, v3, vcc
	s_add_u32 s2, s20, s2
	v_sub_f32_e32 v1, v1, v2
	s_addc_u32 s3, s21, s3
	v_lshlrev_b64 v[2:3], 6, v[136:137]
	v_lshl_add_u64 v[2:3], s[2:3], 0, v[2:3]
	s_lshl_b32 s26, s53, 2
	v_add_f32_e32 v1, v164, v1
	v_lshl_add_u64 v[2:3], v[2:3], 0, s[26:27]
	global_store_dword v[2:3], v1, off
	s_branch .LBB0_267
